# v7: + diff passes take the running-max subtraction through the QK MFMA C operand and touch the K/V lines of tile it+2 one trip early
# speedup vs baseline: 1.0323x; 1.0069x over previous
.LBB0_2038:
	s_or_b64 exec, exec, s[6:7]
	s_lshl_b32 s56, s19, 1
	v_lshl_add_u64 v[2:3], v[140:141], 0, s[56:57]
	global_load_dwordx4 v[132:135], v[2:3], off
	s_add_i32 s19, s21, 1
	s_add_i32 s22, s35, -1
	s_min_u32 s19, s19, s22
	s_lshl_b32 s19, s19, 6
	s_add_i32 s56, s19, s29
	s_lshl_b64 s[22:23], s[56:57], 6
	v_lshl_add_u64 v[2:3], v[146:147], 0, s[22:23]
	global_load_dword v14, v[2:3], off
	s_lshl_b32 s56, s19, 1
	v_lshl_add_u64 v[2:3], v[140:141], 0, s[56:57]
	global_load_dword v148, v[2:3], off
.LBB0_2039:
	v_cndmask_b32_e64 v2, 0, 1, s[14:15]
	v_cmp_ne_u32_e64 s[6:7], 1, v2
	s_andn2_b64 vcc, exec, s[14:15]
	s_cbranch_vccnz .LBB0_2046
	s_cmp_eq_u32 s18, 0
	s_cselect_b32 s19, 1, 0
	s_bitcmp1_b32 s18, 0
	s_cselect_b32 s18, 0x5800, 0
	v_add3_u32 v15, s18, v251, v156
	v_add3_u32 v183, s18, v239, v155
	v_add_u32_e32 v187, 0x4600, v183
	v_add_u32_e32 v183, 0x3400, v183
	s_cmp_lg_u32 s19, 0
	s_cbranch_scc0 .Lnoinit_diff1c
	v_mov_b32_e32 v196, 0
	v_mov_b32_e32 v197, 0
	v_mov_b32_e32 v198, 0
	v_mov_b32_e32 v199, 0
	v_mov_b32_e32 v200, 0
	v_mov_b32_e32 v201, 0
	v_mov_b32_e32 v202, 0
	v_mov_b32_e32 v203, 0
	v_mov_b32_e32 v204, 0
	v_mov_b32_e32 v205, 0
	v_mov_b32_e32 v206, 0
	v_mov_b32_e32 v207, 0
	v_mov_b32_e32 v208, 0
	v_mov_b32_e32 v209, 0
	v_mov_b32_e32 v210, 0
	v_mov_b32_e32 v211, 0
	v_mov_b32_e32 v212, 0
	v_mov_b32_e32 v213, 0
	v_mov_b32_e32 v214, 0
	v_mov_b32_e32 v215, 0
	v_mov_b32_e32 v216, 0
	v_mov_b32_e32 v217, 0
	v_mov_b32_e32 v218, 0
	v_mov_b32_e32 v219, 0
	v_mov_b32_e32 v220, 0
	v_mov_b32_e32 v221, 0
	v_mov_b32_e32 v222, 0
	v_mov_b32_e32 v223, 0
	v_mov_b32_e32 v224, 0
	v_mov_b32_e32 v225, 0
	v_mov_b32_e32 v226, 0
	v_mov_b32_e32 v227, 0
.Lnoinit_diff1c:
	ds_read_b128 v[2:5], v15 offset:0
	ds_read_b128 v[6:9], v15 offset:32
	ds_read2_b64 v[10:13], v183 offset0:0 offset1:2
	ds_read2_b64 v[136:139], v183 offset0:4 offset1:6
	ds_read2_b64 v[150:153], v187 offset0:0 offset1:2
	ds_read2_b64 v[190:193], v187 offset0:4 offset1:6
	s_waitcnt lgkmcnt(5)
	v_mfma_f32_32x32x16_f16 v[96:111], v[2:5], v[112:115], v[196:211]
	s_waitcnt lgkmcnt(4)
	v_mfma_f32_32x32x16_f16 v[96:111], v[6:9], v[116:119], v[96:111]
	s_nop 11
	v_max3_f32 v189, v96, v97, v98
	v_max3_f32 v194, v99, v100, v101
	v_max3_f32 v189, v189, v102, v103
	v_max3_f32 v194, v194, v104, v105
	v_max3_f32 v189, v189, v106, v107
	v_max3_f32 v194, v194, v108, v109
	v_max3_f32 v189, v189, v110, v111
	v_max_f32_e32 v189, v189, v194
	v_mov_b32_e32 v194, v189
	v_mfma_f32_32x32x16_f16 v[80:95], v[2:5], v[120:123], v[212:227]
	s_nop 0
	v_permlane32_swap_b32_e32 v194, v189
	v_max_f32_e32 v189, v189, v194
	v_cmp_lt_f32_e32 vcc, 0x41000000, v189
	s_cmp_lg_u32 s19, 0
	s_cbranch_scc1 .Lresc1st_diff1c_0
	s_cbranch_vccnz .Lresc_diff1c_0
.Lcont_diff1c_0:
	v_exp_f32_e32 v96, v96
	v_exp_f32_e32 v97, v97
	v_exp_f32_e32 v98, v98
	v_exp_f32_e32 v99, v99
	v_exp_f32_e32 v100, v100
	v_exp_f32_e32 v101, v101
	v_exp_f32_e32 v102, v102
	v_exp_f32_e32 v103, v103
	v_exp_f32_e32 v104, v104
	v_exp_f32_e32 v105, v105
	v_exp_f32_e32 v106, v106
	v_exp_f32_e32 v107, v107
	v_mfma_f32_32x32x16_f16 v[80:95], v[6:9], v[124:127], v[80:95]
	v_exp_f32_e32 v108, v108
	v_exp_f32_e32 v109, v109
	v_exp_f32_e32 v110, v110
	v_exp_f32_e32 v111, v111
	v_cvt_pk_f16_f32 v228, v96, v97
	v_cvt_pk_f16_f32 v229, v98, v99
	v_cvt_pk_f16_f32 v230, v100, v101
	v_cvt_pk_f16_f32 v231, v102, v103
	v_cvt_pk_f16_f32 v232, v104, v105
	v_cvt_pk_f16_f32 v233, v106, v107
	v_cvt_pk_f16_f32 v234, v108, v109
	v_cvt_pk_f16_f32 v235, v110, v111
	v_pk_add_f32 v[96:97], v[96:97], v[98:99]
	v_pk_add_f32 v[100:101], v[100:101], v[102:103]
	v_pk_add_f32 v[104:105], v[104:105], v[106:107]
	v_pk_add_f32 v[108:109], v[108:109], v[110:111]
	v_pk_add_f32 v[96:97], v[96:97], v[100:101]
	v_pk_add_f32 v[104:105], v[104:105], v[108:109]
	v_pk_add_f32 v[96:97], v[96:97], v[104:105]
	v_add_f32_e32 v96, v96, v97
	v_add_f32_e32 v149, v149, v96
	ds_read_b128 v[2:5], v15 offset:2560
	ds_read_b128 v[6:9], v15 offset:2592
	v_max3_f32 v189, v80, v81, v82
	v_max3_f32 v194, v83, v84, v85
	v_max3_f32 v189, v189, v86, v87
	v_max3_f32 v194, v194, v88, v89
	s_waitcnt lgkmcnt(5)
	v_mfma_f32_32x32x16_f16 v[64:79], v[10:13], v[228:231], v[64:79]
	v_max3_f32 v189, v189, v90, v91
	v_max3_f32 v194, v194, v92, v93
	v_max3_f32 v189, v189, v94, v95
	v_max_f32_e32 v189, v189, v194
	v_mov_b32_e32 v194, v189
	s_nop 1
	v_permlane32_swap_b32_e32 v194, v189
	v_max_f32_e32 v189, v189, v194
	s_waitcnt lgkmcnt(3)
	v_mfma_f32_32x32x16_f16 v[32:47], v[150:153], v[228:231], v[32:47]
	v_cmp_lt_f32_e32 vcc, 0x41000000, v189
	s_cmp_lg_u32 s19, 0
	s_cbranch_scc1 .Lresc1st_diff1c_1
	s_cbranch_vccnz .Lresc_diff1c_1
.Lcont_diff1c_1:
	v_exp_f32_e32 v80, v80
	v_exp_f32_e32 v81, v81
	v_exp_f32_e32 v82, v82
	v_exp_f32_e32 v83, v83
	v_exp_f32_e32 v84, v84
	v_exp_f32_e32 v85, v85
	v_mfma_f32_32x32x16_f16 v[64:79], v[136:139], v[232:235], v[64:79]
	v_exp_f32_e32 v86, v86
	v_exp_f32_e32 v87, v87
	v_exp_f32_e32 v88, v88
	v_exp_f32_e32 v89, v89
	v_exp_f32_e32 v90, v90
	v_exp_f32_e32 v91, v91
	v_exp_f32_e32 v92, v92
	s_waitcnt lgkmcnt(2)
	v_mfma_f32_32x32x16_f16 v[32:47], v[190:193], v[232:235], v[32:47]
	v_exp_f32_e32 v93, v93
	v_exp_f32_e32 v94, v94
	v_exp_f32_e32 v95, v95
	v_cvt_pk_f16_f32 v228, v80, v81
	s_waitcnt lgkmcnt(1)
	v_mfma_f32_32x32x16_f16 v[96:111], v[2:5], v[112:115], v[196:211]
	v_cvt_pk_f16_f32 v229, v82, v83
	v_cvt_pk_f16_f32 v230, v84, v85
	s_waitcnt lgkmcnt(0)
	v_mfma_f32_32x32x16_f16 v[96:111], v[6:9], v[116:119], v[96:111]
	v_cvt_pk_f16_f32 v231, v86, v87
	v_cvt_pk_f16_f32 v232, v88, v89
	v_cvt_pk_f16_f32 v233, v90, v91
	v_cvt_pk_f16_f32 v234, v92, v93
	v_cvt_pk_f16_f32 v235, v94, v95
	v_pk_add_f32 v[80:81], v[80:81], v[82:83]
	v_pk_add_f32 v[84:85], v[84:85], v[86:87]
	v_pk_add_f32 v[88:89], v[88:89], v[90:91]
	v_pk_add_f32 v[92:93], v[92:93], v[94:95]
	v_pk_add_f32 v[80:81], v[80:81], v[84:85]
	v_pk_add_f32 v[88:89], v[88:89], v[92:93]
	v_pk_add_f32 v[80:81], v[80:81], v[88:89]
	v_add_f32_e32 v80, v80, v81
	v_add_f32_e32 v1, v1, v80
	v_max3_f32 v189, v96, v97, v98
	v_max3_f32 v194, v99, v100, v101
	v_max3_f32 v189, v189, v102, v103
	v_max3_f32 v194, v194, v104, v105
	v_mfma_f32_32x32x16_f16 v[48:63], v[10:13], v[228:231], v[48:63]
	v_max3_f32 v189, v189, v106, v107
	v_max3_f32 v194, v194, v108, v109
	v_max3_f32 v189, v189, v110, v111
	v_max_f32_e32 v189, v189, v194
	v_mov_b32_e32 v194, v189
	s_nop 1
	v_permlane32_swap_b32_e32 v194, v189
	v_max_f32_e32 v189, v189, v194
	v_mfma_f32_32x32x16_f16 v[16:31], v[150:153], v[228:231], v[16:31]
	v_cmp_lt_f32_e32 vcc, 0x41000000, v189
	s_cbranch_vccnz .Lresc_diff1c_2
; template <int DQ, bool NA, int NQG>
; DI void attn_wg(const half_t* Qp, const half_t* Kp, const half_t* Vp, int q0, bool active, int seg0_start, int seg0_tiles,
;                 int seg1_start, int seg1_tiles, const float* rpb_h, int rq, char* smem, int tid, f16v (&O)[2][NQG]) {
;     ...
;         for (int qg = 0; qg < NQG; ++qg) {
;           h8 P[2];
;           float mx = S[qg][0];
; #pragma unroll
;           for (int i = 1; i < 16; ++i) mx = fmaxf(mx, S[qg][i]);
;           mx = fmaxf(mx, __shfl_xor(mx, 32));
;           if (__builtin_amdgcn_ballot_w64(mx > mrun[qg] + 8.f) != 0ull) {
;             const float mnew = fmaxf(mrun[qg], mx);
;             const float alpha = __builtin_amdgcn_exp2f(mrun[qg] - mnew);
;             lrun[qg] *= alpha;
; #pragma unroll
;             for (int dvt = 0; dvt < 2; ++dvt)
; #pragma unroll
;               for (int i = 0; i < 16; ++i) O[dvt][qg][i] *= alpha;
;             mrun[qg] = mnew;
;           }
;           const float mn = mrun[qg];
;           f2 rs2 = {0.f, 0.f};
;           const f2 mn2 = {mn, mn};
; #pragma unroll
;           for (int i = 0; i < 16; i += 2) {
;             const f2 s2 = {S[qg][i], S[qg][i + 1]};
;             const f2 d2 = s2 - mn2;
;             f2 p2;
;             p2.x = __builtin_amdgcn_exp2f(d2.x);
;             p2.y = __builtin_amdgcn_exp2f(d2.y);
;             if (NA) { p2.x = (s2.x <= -1e29f) ? 0.f : p2.x; p2.y = (s2.y <= -1e29f) ? 0.f : p2.y; }
;             rs2 += p2;
;             P[i >> 3][i & 7] = (half_t)p2.x;
;             P[i >> 3][(i & 7) + 1] = (half_t)p2.y;
;           }
;           lrun[qg] += rs2.x + rs2.y;
; #pragma unroll
;           for (int dvt = 0; dvt < 2; ++dvt) {
; #pragma unroll
;             for (int sx = 0; sx < 2; ++sx) {
;               const h8 va = __builtin_shufflevector(vf[dvt][sx][0], vf[dvt][sx][1], 0, 1, 2, 3, 4, 5, 6, 7);
;               O[dvt][qg] = __builtin_amdgcn_mfma_f32_32x32x16_f16(va, P[sx], O[dvt][qg], 0, 0, 0);
;             }
;           }
;         }
.Lcont_diff1c_2:
	v_exp_f32_e32 v96, v96
	v_exp_f32_e32 v97, v97
	v_exp_f32_e32 v98, v98
	v_exp_f32_e32 v99, v99
	v_exp_f32_e32 v100, v100
	v_exp_f32_e32 v101, v101
	v_mfma_f32_32x32x16_f16 v[48:63], v[136:139], v[232:235], v[48:63]
	v_exp_f32_e32 v102, v102
	v_exp_f32_e32 v103, v103
	v_exp_f32_e32 v104, v104
	v_exp_f32_e32 v105, v105
	v_exp_f32_e32 v106, v106
	v_exp_f32_e32 v107, v107
	v_exp_f32_e32 v108, v108
	v_mfma_f32_32x32x16_f16 v[16:31], v[190:193], v[232:235], v[16:31]
	ds_read2_b64 v[10:13], v183 offset0:8 offset1:10
	ds_read2_b64 v[136:139], v183 offset0:12 offset1:14
	ds_read2_b64 v[150:153], v187 offset0:8 offset1:10
	ds_read2_b64 v[190:193], v187 offset0:12 offset1:14
	v_exp_f32_e32 v109, v109
	v_exp_f32_e32 v110, v110
	v_exp_f32_e32 v111, v111
	v_cvt_pk_f16_f32 v228, v96, v97
	v_mfma_f32_32x32x16_f16 v[80:95], v[2:5], v[120:123], v[212:227]
	v_cvt_pk_f16_f32 v229, v98, v99
	v_cvt_pk_f16_f32 v230, v100, v101
	v_mfma_f32_32x32x16_f16 v[80:95], v[6:9], v[124:127], v[80:95]
	v_cvt_pk_f16_f32 v231, v102, v103
	v_cvt_pk_f16_f32 v232, v104, v105
	v_cvt_pk_f16_f32 v233, v106, v107
	v_cvt_pk_f16_f32 v234, v108, v109
	v_cvt_pk_f16_f32 v235, v110, v111
	v_pk_add_f32 v[96:97], v[96:97], v[98:99]
	v_pk_add_f32 v[100:101], v[100:101], v[102:103]
	v_pk_add_f32 v[104:105], v[104:105], v[106:107]
	v_pk_add_f32 v[108:109], v[108:109], v[110:111]
	v_pk_add_f32 v[96:97], v[96:97], v[100:101]
	v_pk_add_f32 v[104:105], v[104:105], v[108:109]
	v_pk_add_f32 v[96:97], v[96:97], v[104:105]
	v_add_f32_e32 v96, v96, v97
	v_add_f32_e32 v149, v149, v96
	v_max3_f32 v189, v80, v81, v82
	v_max3_f32 v194, v83, v84, v85
	v_max3_f32 v189, v189, v86, v87
	v_max3_f32 v194, v194, v88, v89
	s_waitcnt lgkmcnt(3)
	v_mfma_f32_32x32x16_f16 v[64:79], v[10:13], v[228:231], v[64:79]
	v_max3_f32 v189, v189, v90, v91
	v_max3_f32 v194, v194, v92, v93
	v_max3_f32 v189, v189, v94, v95
	v_max_f32_e32 v189, v189, v194
	v_mov_b32_e32 v194, v189
	s_nop 1
	v_permlane32_swap_b32_e32 v194, v189
	v_max_f32_e32 v189, v189, v194
	s_waitcnt lgkmcnt(1)
	v_mfma_f32_32x32x16_f16 v[32:47], v[150:153], v[228:231], v[32:47]
	v_cmp_lt_f32_e32 vcc, 0x41000000, v189
	s_cbranch_vccnz .Lresc_diff1c_3
.Lcont_diff1c_3:
	v_exp_f32_e32 v80, v80
	v_exp_f32_e32 v81, v81
	v_exp_f32_e32 v82, v82
	v_exp_f32_e32 v83, v83
	v_exp_f32_e32 v84, v84
	v_exp_f32_e32 v85, v85
	v_mfma_f32_32x32x16_f16 v[64:79], v[136:139], v[232:235], v[64:79]
	v_exp_f32_e32 v86, v86
	v_exp_f32_e32 v87, v87
	v_exp_f32_e32 v88, v88
	v_exp_f32_e32 v89, v89
	v_exp_f32_e32 v90, v90
	v_exp_f32_e32 v91, v91
	v_exp_f32_e32 v92, v92
	s_waitcnt lgkmcnt(0)
	v_mfma_f32_32x32x16_f16 v[32:47], v[190:193], v[232:235], v[32:47]
	v_exp_f32_e32 v93, v93
	v_exp_f32_e32 v94, v94
	v_exp_f32_e32 v95, v95
	v_cvt_pk_f16_f32 v228, v80, v81
	v_cvt_pk_f16_f32 v229, v82, v83
	v_cvt_pk_f16_f32 v230, v84, v85
	v_cvt_pk_f16_f32 v231, v86, v87
	v_cvt_pk_f16_f32 v232, v88, v89
	v_cvt_pk_f16_f32 v233, v90, v91
	v_cvt_pk_f16_f32 v234, v92, v93
	v_cvt_pk_f16_f32 v235, v94, v95
	v_pk_add_f32 v[80:81], v[80:81], v[82:83]
	v_pk_add_f32 v[84:85], v[84:85], v[86:87]
	v_pk_add_f32 v[88:89], v[88:89], v[90:91]
	v_pk_add_f32 v[92:93], v[92:93], v[94:95]
	v_pk_add_f32 v[80:81], v[80:81], v[84:85]
	v_pk_add_f32 v[88:89], v[88:89], v[92:93]
	v_pk_add_f32 v[80:81], v[80:81], v[88:89]
	v_add_f32_e32 v80, v80, v81
	v_add_f32_e32 v1, v1, v80
	v_mfma_f32_32x32x16_f16 v[48:63], v[10:13], v[228:231], v[48:63]
	v_mfma_f32_32x32x16_f16 v[16:31], v[150:153], v[228:231], v[16:31]
	v_mfma_f32_32x32x16_f16 v[48:63], v[136:139], v[232:235], v[48:63]
	v_mfma_f32_32x32x16_f16 v[16:31], v[190:193], v[232:235], v[16:31]
	s_branch .Lend_diff1c
.Lresc1st_diff1c_0:
	v_mov_b32_e32 v194, v189
	s_nop 11
	v_pk_add_f32 v[196:197], v[196:197], v[194:195] op_sel_hi:[1,0] neg_lo:[0,1] neg_hi:[0,1]
	v_pk_add_f32 v[198:199], v[198:199], v[194:195] op_sel_hi:[1,0] neg_lo:[0,1] neg_hi:[0,1]
	v_pk_add_f32 v[200:201], v[200:201], v[194:195] op_sel_hi:[1,0] neg_lo:[0,1] neg_hi:[0,1]
	v_pk_add_f32 v[202:203], v[202:203], v[194:195] op_sel_hi:[1,0] neg_lo:[0,1] neg_hi:[0,1]
	v_pk_add_f32 v[204:205], v[204:205], v[194:195] op_sel_hi:[1,0] neg_lo:[0,1] neg_hi:[0,1]
	v_pk_add_f32 v[206:207], v[206:207], v[194:195] op_sel_hi:[1,0] neg_lo:[0,1] neg_hi:[0,1]
	v_pk_add_f32 v[208:209], v[208:209], v[194:195] op_sel_hi:[1,0] neg_lo:[0,1] neg_hi:[0,1]
	v_pk_add_f32 v[210:211], v[210:211], v[194:195] op_sel_hi:[1,0] neg_lo:[0,1] neg_hi:[0,1]
	v_pk_add_f32 v[96:97], v[96:97], v[194:195] op_sel_hi:[1,0] neg_lo:[0,1] neg_hi:[0,1]
	v_pk_add_f32 v[98:99], v[98:99], v[194:195] op_sel_hi:[1,0] neg_lo:[0,1] neg_hi:[0,1]
	v_pk_add_f32 v[100:101], v[100:101], v[194:195] op_sel_hi:[1,0] neg_lo:[0,1] neg_hi:[0,1]
	v_pk_add_f32 v[102:103], v[102:103], v[194:195] op_sel_hi:[1,0] neg_lo:[0,1] neg_hi:[0,1]
	v_pk_add_f32 v[104:105], v[104:105], v[194:195] op_sel_hi:[1,0] neg_lo:[0,1] neg_hi:[0,1]
	v_pk_add_f32 v[106:107], v[106:107], v[194:195] op_sel_hi:[1,0] neg_lo:[0,1] neg_hi:[0,1]
	v_pk_add_f32 v[108:109], v[108:109], v[194:195] op_sel_hi:[1,0] neg_lo:[0,1] neg_hi:[0,1]
	v_pk_add_f32 v[110:111], v[110:111], v[194:195] op_sel_hi:[1,0] neg_lo:[0,1] neg_hi:[0,1]
	s_branch .Lcont_diff1c_0
; template <int DQ, bool NA, int NQG>
; DI void attn_wg(const half_t* Qp, const half_t* Kp, const half_t* Vp, int q0, bool active, int seg0_start, int seg0_tiles,
;                 int seg1_start, int seg1_tiles, const float* rpb_h, int rq, char* smem, int tid, f16v (&O)[2][NQG]) {
;     ...
;           if (__builtin_amdgcn_ballot_w64(mx > mrun[qg] + 8.f) != 0ull) {
;             const float mnew = fmaxf(mrun[qg], mx);
;             const float alpha = __builtin_amdgcn_exp2f(mrun[qg] - mnew);
;             lrun[qg] *= alpha;
; #pragma unroll
;             for (int dvt = 0; dvt < 2; ++dvt)
; #pragma unroll
;               for (int i = 0; i < 16; ++i) O[dvt][qg][i] *= alpha;
;             mrun[qg] = mnew;
;           }
;           const float mn = mrun[qg];
;           f2 rs2 = {0.f, 0.f};
;           const f2 mn2 = {mn, mn};
.Lresc_diff1c_0:
	v_max_f32_e32 v194, 0, v189
	s_nop 11
	v_pk_add_f32 v[196:197], v[196:197], v[194:195] op_sel_hi:[1,0] neg_lo:[0,1] neg_hi:[0,1]
	v_pk_add_f32 v[198:199], v[198:199], v[194:195] op_sel_hi:[1,0] neg_lo:[0,1] neg_hi:[0,1]
	v_pk_add_f32 v[200:201], v[200:201], v[194:195] op_sel_hi:[1,0] neg_lo:[0,1] neg_hi:[0,1]
	v_pk_add_f32 v[202:203], v[202:203], v[194:195] op_sel_hi:[1,0] neg_lo:[0,1] neg_hi:[0,1]
	v_pk_add_f32 v[204:205], v[204:205], v[194:195] op_sel_hi:[1,0] neg_lo:[0,1] neg_hi:[0,1]
	v_pk_add_f32 v[206:207], v[206:207], v[194:195] op_sel_hi:[1,0] neg_lo:[0,1] neg_hi:[0,1]
	v_pk_add_f32 v[208:209], v[208:209], v[194:195] op_sel_hi:[1,0] neg_lo:[0,1] neg_hi:[0,1]
	v_pk_add_f32 v[210:211], v[210:211], v[194:195] op_sel_hi:[1,0] neg_lo:[0,1] neg_hi:[0,1]
	v_pk_add_f32 v[96:97], v[96:97], v[194:195] op_sel_hi:[1,0] neg_lo:[0,1] neg_hi:[0,1]
	v_pk_add_f32 v[98:99], v[98:99], v[194:195] op_sel_hi:[1,0] neg_lo:[0,1] neg_hi:[0,1]
	v_pk_add_f32 v[100:101], v[100:101], v[194:195] op_sel_hi:[1,0] neg_lo:[0,1] neg_hi:[0,1]
	v_pk_add_f32 v[102:103], v[102:103], v[194:195] op_sel_hi:[1,0] neg_lo:[0,1] neg_hi:[0,1]
	v_pk_add_f32 v[104:105], v[104:105], v[194:195] op_sel_hi:[1,0] neg_lo:[0,1] neg_hi:[0,1]
	v_pk_add_f32 v[106:107], v[106:107], v[194:195] op_sel_hi:[1,0] neg_lo:[0,1] neg_hi:[0,1]
	v_pk_add_f32 v[108:109], v[108:109], v[194:195] op_sel_hi:[1,0] neg_lo:[0,1] neg_hi:[0,1]
	v_pk_add_f32 v[110:111], v[110:111], v[194:195] op_sel_hi:[1,0] neg_lo:[0,1] neg_hi:[0,1]
	v_exp_f32_e64 v194, -v194
	s_nop 0
	v_mul_f32_e32 v149, v149, v194
	v_pk_mul_f32 v[64:65], v[64:65], v[194:195] op_sel_hi:[1,0]
	v_pk_mul_f32 v[66:67], v[66:67], v[194:195] op_sel_hi:[1,0]
	v_pk_mul_f32 v[68:69], v[68:69], v[194:195] op_sel_hi:[1,0]
	v_pk_mul_f32 v[70:71], v[70:71], v[194:195] op_sel_hi:[1,0]
	v_pk_mul_f32 v[72:73], v[72:73], v[194:195] op_sel_hi:[1,0]
	v_pk_mul_f32 v[74:75], v[74:75], v[194:195] op_sel_hi:[1,0]
	v_pk_mul_f32 v[76:77], v[76:77], v[194:195] op_sel_hi:[1,0]
	v_pk_mul_f32 v[78:79], v[78:79], v[194:195] op_sel_hi:[1,0]
	v_pk_mul_f32 v[32:33], v[32:33], v[194:195] op_sel_hi:[1,0]
	v_pk_mul_f32 v[34:35], v[34:35], v[194:195] op_sel_hi:[1,0]
	v_pk_mul_f32 v[36:37], v[36:37], v[194:195] op_sel_hi:[1,0]
	v_pk_mul_f32 v[38:39], v[38:39], v[194:195] op_sel_hi:[1,0]
	v_pk_mul_f32 v[40:41], v[40:41], v[194:195] op_sel_hi:[1,0]
	v_pk_mul_f32 v[42:43], v[42:43], v[194:195] op_sel_hi:[1,0]
	v_pk_mul_f32 v[44:45], v[44:45], v[194:195] op_sel_hi:[1,0]
	v_pk_mul_f32 v[46:47], v[46:47], v[194:195] op_sel_hi:[1,0]
	s_branch .Lcont_diff1c_0
.Lresc1st_diff1c_1:
	v_mov_b32_e32 v194, v189
	s_nop 11
	v_pk_add_f32 v[212:213], v[212:213], v[194:195] op_sel_hi:[1,0] neg_lo:[0,1] neg_hi:[0,1]
	v_pk_add_f32 v[214:215], v[214:215], v[194:195] op_sel_hi:[1,0] neg_lo:[0,1] neg_hi:[0,1]
	v_pk_add_f32 v[216:217], v[216:217], v[194:195] op_sel_hi:[1,0] neg_lo:[0,1] neg_hi:[0,1]
	v_pk_add_f32 v[218:219], v[218:219], v[194:195] op_sel_hi:[1,0] neg_lo:[0,1] neg_hi:[0,1]
	v_pk_add_f32 v[220:221], v[220:221], v[194:195] op_sel_hi:[1,0] neg_lo:[0,1] neg_hi:[0,1]
	v_pk_add_f32 v[222:223], v[222:223], v[194:195] op_sel_hi:[1,0] neg_lo:[0,1] neg_hi:[0,1]
	v_pk_add_f32 v[224:225], v[224:225], v[194:195] op_sel_hi:[1,0] neg_lo:[0,1] neg_hi:[0,1]
	v_pk_add_f32 v[226:227], v[226:227], v[194:195] op_sel_hi:[1,0] neg_lo:[0,1] neg_hi:[0,1]
	v_pk_add_f32 v[80:81], v[80:81], v[194:195] op_sel_hi:[1,0] neg_lo:[0,1] neg_hi:[0,1]
	v_pk_add_f32 v[82:83], v[82:83], v[194:195] op_sel_hi:[1,0] neg_lo:[0,1] neg_hi:[0,1]
	v_pk_add_f32 v[84:85], v[84:85], v[194:195] op_sel_hi:[1,0] neg_lo:[0,1] neg_hi:[0,1]
	v_pk_add_f32 v[86:87], v[86:87], v[194:195] op_sel_hi:[1,0] neg_lo:[0,1] neg_hi:[0,1]
	v_pk_add_f32 v[88:89], v[88:89], v[194:195] op_sel_hi:[1,0] neg_lo:[0,1] neg_hi:[0,1]
	v_pk_add_f32 v[90:91], v[90:91], v[194:195] op_sel_hi:[1,0] neg_lo:[0,1] neg_hi:[0,1]
	v_pk_add_f32 v[92:93], v[92:93], v[194:195] op_sel_hi:[1,0] neg_lo:[0,1] neg_hi:[0,1]
	v_pk_add_f32 v[94:95], v[94:95], v[194:195] op_sel_hi:[1,0] neg_lo:[0,1] neg_hi:[0,1]
	s_branch .Lcont_diff1c_1
.Lresc_diff1c_1:
	v_max_f32_e32 v194, 0, v189
	s_nop 11
	v_pk_add_f32 v[212:213], v[212:213], v[194:195] op_sel_hi:[1,0] neg_lo:[0,1] neg_hi:[0,1]
	v_pk_add_f32 v[214:215], v[214:215], v[194:195] op_sel_hi:[1,0] neg_lo:[0,1] neg_hi:[0,1]
	v_pk_add_f32 v[216:217], v[216:217], v[194:195] op_sel_hi:[1,0] neg_lo:[0,1] neg_hi:[0,1]
	v_pk_add_f32 v[218:219], v[218:219], v[194:195] op_sel_hi:[1,0] neg_lo:[0,1] neg_hi:[0,1]
	v_pk_add_f32 v[220:221], v[220:221], v[194:195] op_sel_hi:[1,0] neg_lo:[0,1] neg_hi:[0,1]
	v_pk_add_f32 v[222:223], v[222:223], v[194:195] op_sel_hi:[1,0] neg_lo:[0,1] neg_hi:[0,1]
	v_pk_add_f32 v[224:225], v[224:225], v[194:195] op_sel_hi:[1,0] neg_lo:[0,1] neg_hi:[0,1]
	v_pk_add_f32 v[226:227], v[226:227], v[194:195] op_sel_hi:[1,0] neg_lo:[0,1] neg_hi:[0,1]
	v_pk_add_f32 v[80:81], v[80:81], v[194:195] op_sel_hi:[1,0] neg_lo:[0,1] neg_hi:[0,1]
	v_pk_add_f32 v[82:83], v[82:83], v[194:195] op_sel_hi:[1,0] neg_lo:[0,1] neg_hi:[0,1]
	v_pk_add_f32 v[84:85], v[84:85], v[194:195] op_sel_hi:[1,0] neg_lo:[0,1] neg_hi:[0,1]
	v_pk_add_f32 v[86:87], v[86:87], v[194:195] op_sel_hi:[1,0] neg_lo:[0,1] neg_hi:[0,1]
	v_pk_add_f32 v[88:89], v[88:89], v[194:195] op_sel_hi:[1,0] neg_lo:[0,1] neg_hi:[0,1]
	v_pk_add_f32 v[90:91], v[90:91], v[194:195] op_sel_hi:[1,0] neg_lo:[0,1] neg_hi:[0,1]
	v_pk_add_f32 v[92:93], v[92:93], v[194:195] op_sel_hi:[1,0] neg_lo:[0,1] neg_hi:[0,1]
	v_pk_add_f32 v[94:95], v[94:95], v[194:195] op_sel_hi:[1,0] neg_lo:[0,1] neg_hi:[0,1]
	v_exp_f32_e64 v194, -v194
	s_nop 0
	v_mul_f32_e32 v1, v1, v194
	v_pk_mul_f32 v[48:49], v[48:49], v[194:195] op_sel_hi:[1,0]
	v_pk_mul_f32 v[50:51], v[50:51], v[194:195] op_sel_hi:[1,0]
	v_pk_mul_f32 v[52:53], v[52:53], v[194:195] op_sel_hi:[1,0]
	v_pk_mul_f32 v[54:55], v[54:55], v[194:195] op_sel_hi:[1,0]
	v_pk_mul_f32 v[56:57], v[56:57], v[194:195] op_sel_hi:[1,0]
	v_pk_mul_f32 v[58:59], v[58:59], v[194:195] op_sel_hi:[1,0]
	v_pk_mul_f32 v[60:61], v[60:61], v[194:195] op_sel_hi:[1,0]
	v_pk_mul_f32 v[62:63], v[62:63], v[194:195] op_sel_hi:[1,0]
	v_pk_mul_f32 v[16:17], v[16:17], v[194:195] op_sel_hi:[1,0]
	v_pk_mul_f32 v[18:19], v[18:19], v[194:195] op_sel_hi:[1,0]
	v_pk_mul_f32 v[20:21], v[20:21], v[194:195] op_sel_hi:[1,0]
	v_pk_mul_f32 v[22:23], v[22:23], v[194:195] op_sel_hi:[1,0]
	v_pk_mul_f32 v[24:25], v[24:25], v[194:195] op_sel_hi:[1,0]
	v_pk_mul_f32 v[26:27], v[26:27], v[194:195] op_sel_hi:[1,0]
	v_pk_mul_f32 v[28:29], v[28:29], v[194:195] op_sel_hi:[1,0]
	v_pk_mul_f32 v[30:31], v[30:31], v[194:195] op_sel_hi:[1,0]
	s_branch .Lcont_diff1c_1

; template <int DQ, bool NA, int NQG>
; DI void attn_wg(const half_t* Qp, const half_t* Kp, const half_t* Vp, int q0, bool active, int seg0_start, int seg0_tiles,
;                 int seg1_start, int seg1_tiles, const float* rpb_h, int rq, char* smem, int tid, f16v (&O)[2][NQG]) {
;     ...
;     if (more) {
;       char* nb = smem + ((it + 1) & 1) * ATT_STAGE;
;       if (kc0 < KCH) *(uint4*)((half_t*)nb + ks0) = kreg0;
;       if (DQ == 96 && kc1 < KCH) *(uint4*)((half_t*)nb + ks1) = kreg1;
;       *(uint4*)((half_t*)(nb + ATT_VOFF) + vs0) = vreg;
;     }
;     __syncthreads();
.Lend_diff1c:
.LBB0_2046:
	s_andn2_b64 vcc, exec, s[16:17]
	s_cbranch_vccnz .LBB0_2050
	s_bitcmp1_b32 s21, 0
	s_cselect_b32 s18, 0x5800, 0
	s_and_saveexec_b64 s[16:17], s[4:5]
	s_cbranch_execz .LBB0_2049
	v_lshl_add_u32 v2, v249, 1, s18
	s_waitcnt vmcnt(3)
	ds_write_b128 v2, v[128:131]
.LBB0_2049:
	s_or_b64 exec, exec, s[16:17]
	v_lshl_add_u32 v2, v164, 1, s18
	s_waitcnt vmcnt(2)
	ds_write_b128 v2, v[132:135] offset:13312

.LBB0_2060:
	s_or_b64 exec, exec, s[16:17]
	s_lshl_b32 s56, s20, 1
	v_lshl_add_u64 v[2:3], v[140:141], 0, s[56:57]
	global_load_dwordx4 v[132:135], v[2:3], off
	s_add_i32 s20, s18, 1
	s_add_i32 s22, s35, -1
	s_min_u32 s20, s20, s22
	s_lshl_b32 s20, s20, 6
	s_add_i32 s56, s20, s29
	s_lshl_b64 s[22:23], s[56:57], 6
	v_lshl_add_u64 v[2:3], v[142:143], 0, s[22:23]
	global_load_dword v14, v[2:3], off
	s_lshl_b32 s56, s20, 1
	v_lshl_add_u64 v[2:3], v[140:141], 0, s[56:57]
	global_load_dword v144, v[2:3], off
.LBB0_2061:
	s_and_b64 vcc, exec, s[6:7]
	s_cbranch_vccnz .LBB0_2068
	s_cmp_eq_u32 s19, 0
	s_cselect_b32 s17, 1, 0
	s_bitcmp1_b32 s19, 0
	s_cselect_b32 s16, 0x5800, 0
	v_add3_u32 v15, s16, v251, v156
	v_add3_u32 v151, s16, v239, v155
	v_add_u32_e32 v152, 0x4600, v151
	v_add_u32_e32 v151, 0x3400, v151
	s_cmp_lg_u32 s17, 0
	s_cbranch_scc0 .Lnoinit_diff2c
	v_mov_b32_e32 v196, 0
	v_mov_b32_e32 v197, 0
	v_mov_b32_e32 v198, 0
	v_mov_b32_e32 v199, 0
	v_mov_b32_e32 v200, 0
	v_mov_b32_e32 v201, 0
	v_mov_b32_e32 v202, 0
	v_mov_b32_e32 v203, 0
	v_mov_b32_e32 v204, 0
	v_mov_b32_e32 v205, 0
	v_mov_b32_e32 v206, 0
	v_mov_b32_e32 v207, 0
	v_mov_b32_e32 v208, 0
	v_mov_b32_e32 v209, 0
	v_mov_b32_e32 v210, 0
	v_mov_b32_e32 v211, 0
	v_mov_b32_e32 v212, 0
	v_mov_b32_e32 v213, 0
	v_mov_b32_e32 v214, 0
	v_mov_b32_e32 v215, 0
	v_mov_b32_e32 v216, 0
	v_mov_b32_e32 v217, 0
	v_mov_b32_e32 v218, 0
	v_mov_b32_e32 v219, 0
	v_mov_b32_e32 v220, 0
	v_mov_b32_e32 v221, 0
	v_mov_b32_e32 v222, 0
	v_mov_b32_e32 v223, 0
	v_mov_b32_e32 v224, 0
	v_mov_b32_e32 v225, 0
	v_mov_b32_e32 v226, 0
	v_mov_b32_e32 v227, 0
.Lnoinit_diff2c:
	ds_read_b128 v[2:5], v15 offset:0
	ds_read_b128 v[6:9], v15 offset:32
	ds_read2_b64 v[10:13], v151 offset0:0 offset1:2
	ds_read2_b64 v[136:139], v151 offset0:4 offset1:6
	ds_read2_b64 v[146:149], v152 offset0:0 offset1:2
	ds_read2_b64 v[190:193], v152 offset0:4 offset1:6
	s_waitcnt lgkmcnt(5)
	v_mfma_f32_32x32x16_f16 v[96:111], v[2:5], v[112:115], v[196:211]
	s_waitcnt lgkmcnt(4)
	v_mfma_f32_32x32x16_f16 v[96:111], v[6:9], v[116:119], v[96:111]
	s_nop 11
	v_max3_f32 v189, v96, v97, v98
	v_max3_f32 v194, v99, v100, v101
	v_max3_f32 v189, v189, v102, v103
	v_max3_f32 v194, v194, v104, v105
	v_max3_f32 v189, v189, v106, v107
	v_max3_f32 v194, v194, v108, v109
	v_max3_f32 v189, v189, v110, v111
	v_max_f32_e32 v189, v189, v194
	v_mov_b32_e32 v194, v189
	v_mfma_f32_32x32x16_f16 v[80:95], v[2:5], v[120:123], v[212:227]
	s_nop 0
	v_permlane32_swap_b32_e32 v194, v189
	v_max_f32_e32 v189, v189, v194
	v_cmp_lt_f32_e32 vcc, 0x41000000, v189
	s_cmp_lg_u32 s17, 0
	s_cbranch_scc1 .Lresc1st_diff2c_0
	s_cbranch_vccnz .Lresc_diff2c_0
.Lcont_diff2c_0:
	v_exp_f32_e32 v96, v96
	v_exp_f32_e32 v97, v97
	v_exp_f32_e32 v98, v98
	v_exp_f32_e32 v99, v99
	v_exp_f32_e32 v100, v100
	v_exp_f32_e32 v101, v101
	v_exp_f32_e32 v102, v102
	v_exp_f32_e32 v103, v103
	v_exp_f32_e32 v104, v104
	v_exp_f32_e32 v105, v105
	v_exp_f32_e32 v106, v106
	v_exp_f32_e32 v107, v107
	v_mfma_f32_32x32x16_f16 v[80:95], v[6:9], v[124:127], v[80:95]
	v_exp_f32_e32 v108, v108
	v_exp_f32_e32 v109, v109
	v_exp_f32_e32 v110, v110
	v_exp_f32_e32 v111, v111
	v_cvt_pk_f16_f32 v228, v96, v97
	v_cvt_pk_f16_f32 v229, v98, v99
	v_cvt_pk_f16_f32 v230, v100, v101
	v_cvt_pk_f16_f32 v231, v102, v103
	v_cvt_pk_f16_f32 v232, v104, v105
	v_cvt_pk_f16_f32 v233, v106, v107
	v_cvt_pk_f16_f32 v234, v108, v109
	v_cvt_pk_f16_f32 v235, v110, v111
	v_pk_add_f32 v[96:97], v[96:97], v[98:99]
	v_pk_add_f32 v[100:101], v[100:101], v[102:103]
	v_pk_add_f32 v[104:105], v[104:105], v[106:107]
	v_pk_add_f32 v[108:109], v[108:109], v[110:111]
	v_pk_add_f32 v[96:97], v[96:97], v[100:101]
	v_pk_add_f32 v[104:105], v[104:105], v[108:109]
	v_pk_add_f32 v[96:97], v[96:97], v[104:105]
	v_add_f32_e32 v96, v96, v97
	v_add_f32_e32 v145, v145, v96
	ds_read_b128 v[2:5], v15 offset:2560
	ds_read_b128 v[6:9], v15 offset:2592
	v_max3_f32 v189, v80, v81, v82
	v_max3_f32 v194, v83, v84, v85
	v_max3_f32 v189, v189, v86, v87
	v_max3_f32 v194, v194, v88, v89
	s_waitcnt lgkmcnt(5)
	v_mfma_f32_32x32x16_f16 v[64:79], v[10:13], v[228:231], v[64:79]
	v_max3_f32 v189, v189, v90, v91
	v_max3_f32 v194, v194, v92, v93
	v_max3_f32 v189, v189, v94, v95
	v_max_f32_e32 v189, v189, v194
	v_mov_b32_e32 v194, v189
	s_nop 1
	v_permlane32_swap_b32_e32 v194, v189
	v_max_f32_e32 v189, v189, v194
	s_waitcnt lgkmcnt(3)
	v_mfma_f32_32x32x16_f16 v[48:63], v[146:149], v[228:231], v[48:63]
	v_cmp_lt_f32_e32 vcc, 0x41000000, v189
	s_cmp_lg_u32 s17, 0
	s_cbranch_scc1 .Lresc1st_diff2c_1
	s_cbranch_vccnz .Lresc_diff2c_1
; template <int DQ, bool NA, int NQG>
; DI void attn_wg(const half_t* Qp, const half_t* Kp, const half_t* Vp, int q0, bool active, int seg0_start, int seg0_tiles,
;                 int seg1_start, int seg1_tiles, const float* rpb_h, int rq, char* smem, int tid, f16v (&O)[2][NQG]) {
;     ...
;         for (int qg = 0; qg < NQG; ++qg) {
;           h8 P[2];
;           float mx = S[qg][0];
; #pragma unroll
;           for (int i = 1; i < 16; ++i) mx = fmaxf(mx, S[qg][i]);
;           mx = fmaxf(mx, __shfl_xor(mx, 32));
;           if (__builtin_amdgcn_ballot_w64(mx > mrun[qg] + 8.f) != 0ull) {
;             const float mnew = fmaxf(mrun[qg], mx);
;             const float alpha = __builtin_amdgcn_exp2f(mrun[qg] - mnew);
;             lrun[qg] *= alpha;
; #pragma unroll
;             for (int dvt = 0; dvt < 2; ++dvt)
; #pragma unroll
;               for (int i = 0; i < 16; ++i) O[dvt][qg][i] *= alpha;
;             mrun[qg] = mnew;
;           }
;           const float mn = mrun[qg];
;           f2 rs2 = {0.f, 0.f};
;           const f2 mn2 = {mn, mn};
; #pragma unroll
;           for (int i = 0; i < 16; i += 2) {
;             const f2 s2 = {S[qg][i], S[qg][i + 1]};
;             const f2 d2 = s2 - mn2;
;             f2 p2;
;             p2.x = __builtin_amdgcn_exp2f(d2.x);
;             p2.y = __builtin_amdgcn_exp2f(d2.y);
;             if (NA) { p2.x = (s2.x <= -1e29f) ? 0.f : p2.x; p2.y = (s2.y <= -1e29f) ? 0.f : p2.y; }
;             rs2 += p2;
;             P[i >> 3][i & 7] = (half_t)p2.x;
;             P[i >> 3][(i & 7) + 1] = (half_t)p2.y;
;           }
;           lrun[qg] += rs2.x + rs2.y;
; #pragma unroll
;           for (int dvt = 0; dvt < 2; ++dvt) {
; #pragma unroll
;             for (int sx = 0; sx < 2; ++sx) {
;               const h8 va = __builtin_shufflevector(vf[dvt][sx][0], vf[dvt][sx][1], 0, 1, 2, 3, 4, 5, 6, 7);
;               O[dvt][qg] = __builtin_amdgcn_mfma_f32_32x32x16_f16(va, P[sx], O[dvt][qg], 0, 0, 0);
;             }
;           }
;         }
.Lcont_diff2c_1:
	v_exp_f32_e32 v80, v80
	v_exp_f32_e32 v81, v81
	v_exp_f32_e32 v82, v82
	v_exp_f32_e32 v83, v83
	v_exp_f32_e32 v84, v84
	v_exp_f32_e32 v85, v85
	v_mfma_f32_32x32x16_f16 v[64:79], v[136:139], v[232:235], v[64:79]
	v_exp_f32_e32 v86, v86
	v_exp_f32_e32 v87, v87
	v_exp_f32_e32 v88, v88
	v_exp_f32_e32 v89, v89
	v_exp_f32_e32 v90, v90
	v_exp_f32_e32 v91, v91
	v_exp_f32_e32 v92, v92
	s_waitcnt lgkmcnt(2)
	v_mfma_f32_32x32x16_f16 v[48:63], v[190:193], v[232:235], v[48:63]
	v_exp_f32_e32 v93, v93
	v_exp_f32_e32 v94, v94
	v_exp_f32_e32 v95, v95
	v_cvt_pk_f16_f32 v228, v80, v81
	s_waitcnt lgkmcnt(1)
	v_mfma_f32_32x32x16_f16 v[96:111], v[2:5], v[112:115], v[196:211]
	v_cvt_pk_f16_f32 v229, v82, v83
	v_cvt_pk_f16_f32 v230, v84, v85
	s_waitcnt lgkmcnt(0)
	v_mfma_f32_32x32x16_f16 v[96:111], v[6:9], v[116:119], v[96:111]
	v_cvt_pk_f16_f32 v231, v86, v87
	v_cvt_pk_f16_f32 v232, v88, v89
	v_cvt_pk_f16_f32 v233, v90, v91
	v_cvt_pk_f16_f32 v234, v92, v93
	v_cvt_pk_f16_f32 v235, v94, v95
	v_pk_add_f32 v[80:81], v[80:81], v[82:83]
	v_pk_add_f32 v[84:85], v[84:85], v[86:87]
	v_pk_add_f32 v[88:89], v[88:89], v[90:91]
	v_pk_add_f32 v[92:93], v[92:93], v[94:95]
	v_pk_add_f32 v[80:81], v[80:81], v[84:85]
	v_pk_add_f32 v[88:89], v[88:89], v[92:93]
	v_pk_add_f32 v[80:81], v[80:81], v[88:89]
	v_add_f32_e32 v80, v80, v81
	v_add_f32_e32 v1, v1, v80
	v_max3_f32 v189, v96, v97, v98
	v_max3_f32 v194, v99, v100, v101
	v_max3_f32 v189, v189, v102, v103
	v_max3_f32 v194, v194, v104, v105
	v_mfma_f32_32x32x16_f16 v[32:47], v[10:13], v[228:231], v[32:47]
	v_max3_f32 v189, v189, v106, v107
	v_max3_f32 v194, v194, v108, v109
	v_max3_f32 v189, v189, v110, v111
	v_max_f32_e32 v189, v189, v194
	v_mov_b32_e32 v194, v189
	s_nop 1
	v_permlane32_swap_b32_e32 v194, v189
	v_max_f32_e32 v189, v189, v194
	v_mfma_f32_32x32x16_f16 v[16:31], v[146:149], v[228:231], v[16:31]
	v_cmp_lt_f32_e32 vcc, 0x41000000, v189
	s_cbranch_vccnz .Lresc_diff2c_2
.Lcont_diff2c_2:
	v_exp_f32_e32 v96, v96
	v_exp_f32_e32 v97, v97
	v_exp_f32_e32 v98, v98
	v_exp_f32_e32 v99, v99
	v_exp_f32_e32 v100, v100
	v_exp_f32_e32 v101, v101
	v_mfma_f32_32x32x16_f16 v[32:47], v[136:139], v[232:235], v[32:47]
	v_exp_f32_e32 v102, v102
	v_exp_f32_e32 v103, v103
	v_exp_f32_e32 v104, v104
	v_exp_f32_e32 v105, v105
	v_exp_f32_e32 v106, v106
	v_exp_f32_e32 v107, v107
	v_exp_f32_e32 v108, v108
	v_mfma_f32_32x32x16_f16 v[16:31], v[190:193], v[232:235], v[16:31]
	ds_read2_b64 v[10:13], v151 offset0:8 offset1:10
	ds_read2_b64 v[136:139], v151 offset0:12 offset1:14
	ds_read2_b64 v[146:149], v152 offset0:8 offset1:10
	ds_read2_b64 v[190:193], v152 offset0:12 offset1:14
	v_exp_f32_e32 v109, v109
	v_exp_f32_e32 v110, v110
	v_exp_f32_e32 v111, v111
	v_cvt_pk_f16_f32 v228, v96, v97
	v_mfma_f32_32x32x16_f16 v[80:95], v[2:5], v[120:123], v[212:227]
	v_cvt_pk_f16_f32 v229, v98, v99
	v_cvt_pk_f16_f32 v230, v100, v101
	v_mfma_f32_32x32x16_f16 v[80:95], v[6:9], v[124:127], v[80:95]
	v_cvt_pk_f16_f32 v231, v102, v103
	v_cvt_pk_f16_f32 v232, v104, v105
	v_cvt_pk_f16_f32 v233, v106, v107
	v_cvt_pk_f16_f32 v234, v108, v109
	v_cvt_pk_f16_f32 v235, v110, v111
	v_pk_add_f32 v[96:97], v[96:97], v[98:99]
	v_pk_add_f32 v[100:101], v[100:101], v[102:103]
	v_pk_add_f32 v[104:105], v[104:105], v[106:107]
	v_pk_add_f32 v[108:109], v[108:109], v[110:111]
	v_pk_add_f32 v[96:97], v[96:97], v[100:101]
	v_pk_add_f32 v[104:105], v[104:105], v[108:109]
	v_pk_add_f32 v[96:97], v[96:97], v[104:105]
	v_add_f32_e32 v96, v96, v97
	v_add_f32_e32 v145, v145, v96
	v_max3_f32 v189, v80, v81, v82
	v_max3_f32 v194, v83, v84, v85
	v_max3_f32 v189, v189, v86, v87
	v_max3_f32 v194, v194, v88, v89
	s_waitcnt lgkmcnt(3)
	v_mfma_f32_32x32x16_f16 v[64:79], v[10:13], v[228:231], v[64:79]
	v_max3_f32 v189, v189, v90, v91
	v_max3_f32 v194, v194, v92, v93
	v_max3_f32 v189, v189, v94, v95
	v_max_f32_e32 v189, v189, v194
	v_mov_b32_e32 v194, v189
	s_nop 1
	v_permlane32_swap_b32_e32 v194, v189
	v_max_f32_e32 v189, v189, v194
	s_waitcnt lgkmcnt(1)
	v_mfma_f32_32x32x16_f16 v[48:63], v[146:149], v[228:231], v[48:63]
	v_cmp_lt_f32_e32 vcc, 0x41000000, v189
	s_cbranch_vccnz .Lresc_diff2c_3
.Lcont_diff2c_3:
	v_exp_f32_e32 v80, v80
	v_exp_f32_e32 v81, v81
	v_exp_f32_e32 v82, v82
	v_exp_f32_e32 v83, v83
	v_exp_f32_e32 v84, v84
	v_exp_f32_e32 v85, v85
	v_mfma_f32_32x32x16_f16 v[64:79], v[136:139], v[232:235], v[64:79]
	v_exp_f32_e32 v86, v86
	v_exp_f32_e32 v87, v87
	v_exp_f32_e32 v88, v88
	v_exp_f32_e32 v89, v89
	v_exp_f32_e32 v90, v90
	v_exp_f32_e32 v91, v91
	v_exp_f32_e32 v92, v92
	s_waitcnt lgkmcnt(0)
	v_mfma_f32_32x32x16_f16 v[48:63], v[190:193], v[232:235], v[48:63]
	v_exp_f32_e32 v93, v93
	v_exp_f32_e32 v94, v94
	v_exp_f32_e32 v95, v95
	v_cvt_pk_f16_f32 v228, v80, v81
	v_cvt_pk_f16_f32 v229, v82, v83
	v_cvt_pk_f16_f32 v230, v84, v85
	v_cvt_pk_f16_f32 v231, v86, v87
	v_cvt_pk_f16_f32 v232, v88, v89
	v_cvt_pk_f16_f32 v233, v90, v91
	v_cvt_pk_f16_f32 v234, v92, v93
	v_cvt_pk_f16_f32 v235, v94, v95
	v_pk_add_f32 v[80:81], v[80:81], v[82:83]
	v_pk_add_f32 v[84:85], v[84:85], v[86:87]
	v_pk_add_f32 v[88:89], v[88:89], v[90:91]
	v_pk_add_f32 v[92:93], v[92:93], v[94:95]
	v_pk_add_f32 v[80:81], v[80:81], v[84:85]
	v_pk_add_f32 v[88:89], v[88:89], v[92:93]
	v_pk_add_f32 v[80:81], v[80:81], v[88:89]
	v_add_f32_e32 v80, v80, v81
	v_add_f32_e32 v1, v1, v80
	v_mfma_f32_32x32x16_f16 v[32:47], v[10:13], v[228:231], v[32:47]
	v_mfma_f32_32x32x16_f16 v[16:31], v[146:149], v[228:231], v[16:31]
	v_mfma_f32_32x32x16_f16 v[32:47], v[136:139], v[232:235], v[32:47]
	v_mfma_f32_32x32x16_f16 v[16:31], v[190:193], v[232:235], v[16:31]
	s_branch .Lend_diff2c

; template <int DQ, bool NA, int NQG>
; DI void attn_wg(const half_t* Qp, const half_t* Kp, const half_t* Vp, int q0, bool active, int seg0_start, int seg0_tiles,
;                 int seg1_start, int seg1_tiles, const float* rpb_h, int rq, char* smem, int tid, f16v (&O)[2][NQG]) {
;     ...
;           if (__builtin_amdgcn_ballot_w64(mx > mrun[qg] + 8.f) != 0ull) {
;             const float mnew = fmaxf(mrun[qg], mx);
;             const float alpha = __builtin_amdgcn_exp2f(mrun[qg] - mnew);
;             lrun[qg] *= alpha;
; #pragma unroll
;             for (int dvt = 0; dvt < 2; ++dvt)
; #pragma unroll
;               for (int i = 0; i < 16; ++i) O[dvt][qg][i] *= alpha;
;             mrun[qg] = mnew;
;           }
;           const float mn = mrun[qg];
;           f2 rs2 = {0.f, 0.f};
;           const f2 mn2 = {mn, mn};
.Lresc_diff2c_0:
	v_max_f32_e32 v194, 0, v189
	s_nop 11
	v_pk_add_f32 v[196:197], v[196:197], v[194:195] op_sel_hi:[1,0] neg_lo:[0,1] neg_hi:[0,1]
	v_pk_add_f32 v[198:199], v[198:199], v[194:195] op_sel_hi:[1,0] neg_lo:[0,1] neg_hi:[0,1]
	v_pk_add_f32 v[200:201], v[200:201], v[194:195] op_sel_hi:[1,0] neg_lo:[0,1] neg_hi:[0,1]
	v_pk_add_f32 v[202:203], v[202:203], v[194:195] op_sel_hi:[1,0] neg_lo:[0,1] neg_hi:[0,1]
	v_pk_add_f32 v[204:205], v[204:205], v[194:195] op_sel_hi:[1,0] neg_lo:[0,1] neg_hi:[0,1]
	v_pk_add_f32 v[206:207], v[206:207], v[194:195] op_sel_hi:[1,0] neg_lo:[0,1] neg_hi:[0,1]
	v_pk_add_f32 v[208:209], v[208:209], v[194:195] op_sel_hi:[1,0] neg_lo:[0,1] neg_hi:[0,1]
	v_pk_add_f32 v[210:211], v[210:211], v[194:195] op_sel_hi:[1,0] neg_lo:[0,1] neg_hi:[0,1]
	v_pk_add_f32 v[96:97], v[96:97], v[194:195] op_sel_hi:[1,0] neg_lo:[0,1] neg_hi:[0,1]
	v_pk_add_f32 v[98:99], v[98:99], v[194:195] op_sel_hi:[1,0] neg_lo:[0,1] neg_hi:[0,1]
	v_pk_add_f32 v[100:101], v[100:101], v[194:195] op_sel_hi:[1,0] neg_lo:[0,1] neg_hi:[0,1]
	v_pk_add_f32 v[102:103], v[102:103], v[194:195] op_sel_hi:[1,0] neg_lo:[0,1] neg_hi:[0,1]
	v_pk_add_f32 v[104:105], v[104:105], v[194:195] op_sel_hi:[1,0] neg_lo:[0,1] neg_hi:[0,1]
	v_pk_add_f32 v[106:107], v[106:107], v[194:195] op_sel_hi:[1,0] neg_lo:[0,1] neg_hi:[0,1]
	v_pk_add_f32 v[108:109], v[108:109], v[194:195] op_sel_hi:[1,0] neg_lo:[0,1] neg_hi:[0,1]
	v_pk_add_f32 v[110:111], v[110:111], v[194:195] op_sel_hi:[1,0] neg_lo:[0,1] neg_hi:[0,1]
	v_exp_f32_e64 v194, -v194
	s_nop 0
	v_mul_f32_e32 v145, v145, v194
	v_pk_mul_f32 v[64:65], v[64:65], v[194:195] op_sel_hi:[1,0]
	v_pk_mul_f32 v[66:67], v[66:67], v[194:195] op_sel_hi:[1,0]
	v_pk_mul_f32 v[68:69], v[68:69], v[194:195] op_sel_hi:[1,0]
	v_pk_mul_f32 v[70:71], v[70:71], v[194:195] op_sel_hi:[1,0]
	v_pk_mul_f32 v[72:73], v[72:73], v[194:195] op_sel_hi:[1,0]
	v_pk_mul_f32 v[74:75], v[74:75], v[194:195] op_sel_hi:[1,0]
	v_pk_mul_f32 v[76:77], v[76:77], v[194:195] op_sel_hi:[1,0]
	v_pk_mul_f32 v[78:79], v[78:79], v[194:195] op_sel_hi:[1,0]
	v_pk_mul_f32 v[48:49], v[48:49], v[194:195] op_sel_hi:[1,0]
	v_pk_mul_f32 v[50:51], v[50:51], v[194:195] op_sel_hi:[1,0]
	v_pk_mul_f32 v[52:53], v[52:53], v[194:195] op_sel_hi:[1,0]
	v_pk_mul_f32 v[54:55], v[54:55], v[194:195] op_sel_hi:[1,0]
	v_pk_mul_f32 v[56:57], v[56:57], v[194:195] op_sel_hi:[1,0]
	v_pk_mul_f32 v[58:59], v[58:59], v[194:195] op_sel_hi:[1,0]
	v_pk_mul_f32 v[60:61], v[60:61], v[194:195] op_sel_hi:[1,0]
	v_pk_mul_f32 v[62:63], v[62:63], v[194:195] op_sel_hi:[1,0]
	s_branch .Lcont_diff2c_0

; template <int DQ, bool NA, int NQG>
; DI void attn_wg(const half_t* Qp, const half_t* Kp, const half_t* Vp, int q0, bool active, int seg0_start, int seg0_tiles,
;                 int seg1_start, int seg1_tiles, const float* rpb_h, int rq, char* smem, int tid, f16v (&O)[2][NQG]) {
;     ...
;           if (__builtin_amdgcn_ballot_w64(mx > mrun[qg] + 8.f) != 0ull) {
;             const float mnew = fmaxf(mrun[qg], mx);
;             const float alpha = __builtin_amdgcn_exp2f(mrun[qg] - mnew);
;             lrun[qg] *= alpha;
; #pragma unroll
;             for (int dvt = 0; dvt < 2; ++dvt)
; #pragma unroll
;               for (int i = 0; i < 16; ++i) O[dvt][qg][i] *= alpha;
;             mrun[qg] = mnew;
;           }
;           const float mn = mrun[qg];
;           f2 rs2 = {0.f, 0.f};
;           const f2 mn2 = {mn, mn};
.Lresc_diff2c_1:
	v_max_f32_e32 v194, 0, v189
	s_nop 11
	v_pk_add_f32 v[212:213], v[212:213], v[194:195] op_sel_hi:[1,0] neg_lo:[0,1] neg_hi:[0,1]
	v_pk_add_f32 v[214:215], v[214:215], v[194:195] op_sel_hi:[1,0] neg_lo:[0,1] neg_hi:[0,1]
	v_pk_add_f32 v[216:217], v[216:217], v[194:195] op_sel_hi:[1,0] neg_lo:[0,1] neg_hi:[0,1]
	v_pk_add_f32 v[218:219], v[218:219], v[194:195] op_sel_hi:[1,0] neg_lo:[0,1] neg_hi:[0,1]
	v_pk_add_f32 v[220:221], v[220:221], v[194:195] op_sel_hi:[1,0] neg_lo:[0,1] neg_hi:[0,1]
	v_pk_add_f32 v[222:223], v[222:223], v[194:195] op_sel_hi:[1,0] neg_lo:[0,1] neg_hi:[0,1]
	v_pk_add_f32 v[224:225], v[224:225], v[194:195] op_sel_hi:[1,0] neg_lo:[0,1] neg_hi:[0,1]
	v_pk_add_f32 v[226:227], v[226:227], v[194:195] op_sel_hi:[1,0] neg_lo:[0,1] neg_hi:[0,1]
	v_pk_add_f32 v[80:81], v[80:81], v[194:195] op_sel_hi:[1,0] neg_lo:[0,1] neg_hi:[0,1]
	v_pk_add_f32 v[82:83], v[82:83], v[194:195] op_sel_hi:[1,0] neg_lo:[0,1] neg_hi:[0,1]
	v_pk_add_f32 v[84:85], v[84:85], v[194:195] op_sel_hi:[1,0] neg_lo:[0,1] neg_hi:[0,1]
	v_pk_add_f32 v[86:87], v[86:87], v[194:195] op_sel_hi:[1,0] neg_lo:[0,1] neg_hi:[0,1]
	v_pk_add_f32 v[88:89], v[88:89], v[194:195] op_sel_hi:[1,0] neg_lo:[0,1] neg_hi:[0,1]
	v_pk_add_f32 v[90:91], v[90:91], v[194:195] op_sel_hi:[1,0] neg_lo:[0,1] neg_hi:[0,1]
	v_pk_add_f32 v[92:93], v[92:93], v[194:195] op_sel_hi:[1,0] neg_lo:[0,1] neg_hi:[0,1]
	v_pk_add_f32 v[94:95], v[94:95], v[194:195] op_sel_hi:[1,0] neg_lo:[0,1] neg_hi:[0,1]
	v_exp_f32_e64 v194, -v194
	s_nop 0
	v_mul_f32_e32 v1, v1, v194
	v_pk_mul_f32 v[32:33], v[32:33], v[194:195] op_sel_hi:[1,0]
	v_pk_mul_f32 v[34:35], v[34:35], v[194:195] op_sel_hi:[1,0]
	v_pk_mul_f32 v[36:37], v[36:37], v[194:195] op_sel_hi:[1,0]
	v_pk_mul_f32 v[38:39], v[38:39], v[194:195] op_sel_hi:[1,0]
	v_pk_mul_f32 v[40:41], v[40:41], v[194:195] op_sel_hi:[1,0]
	v_pk_mul_f32 v[42:43], v[42:43], v[194:195] op_sel_hi:[1,0]
	v_pk_mul_f32 v[44:45], v[44:45], v[194:195] op_sel_hi:[1,0]
	v_pk_mul_f32 v[46:47], v[46:47], v[194:195] op_sel_hi:[1,0]
	v_pk_mul_f32 v[16:17], v[16:17], v[194:195] op_sel_hi:[1,0]
	v_pk_mul_f32 v[18:19], v[18:19], v[194:195] op_sel_hi:[1,0]
	v_pk_mul_f32 v[20:21], v[20:21], v[194:195] op_sel_hi:[1,0]
	v_pk_mul_f32 v[22:23], v[22:23], v[194:195] op_sel_hi:[1,0]
	v_pk_mul_f32 v[24:25], v[24:25], v[194:195] op_sel_hi:[1,0]
	v_pk_mul_f32 v[26:27], v[26:27], v[194:195] op_sel_hi:[1,0]
	v_pk_mul_f32 v[28:29], v[28:29], v[194:195] op_sel_hi:[1,0]
	v_pk_mul_f32 v[30:31], v[30:31], v[194:195] op_sel_hi:[1,0]
	s_branch .Lcont_diff2c_1

; template <int DQ, bool NA, int NQG>
; DI void attn_wg(const half_t* Qp, const half_t* Kp, const half_t* Vp, int q0, bool active, int seg0_start, int seg0_tiles,
;                 int seg1_start, int seg1_tiles, const float* rpb_h, int rq, char* smem, int tid, f16v (&O)[2][NQG]) {
;     ...
;     if (more) {
;       char* nb = smem + ((it + 1) & 1) * ATT_STAGE;
;       if (kc0 < KCH) *(uint4*)((half_t*)nb + ks0) = kreg0;
;       if (DQ == 96 && kc1 < KCH) *(uint4*)((half_t*)nb + ks1) = kreg1;
;       *(uint4*)((half_t*)(nb + ATT_VOFF) + vs0) = vreg;
;     }
;     __syncthreads();
.Lend_diff2c:
.LBB0_2068:
	s_andn2_b64 vcc, exec, s[14:15]
	s_cbranch_vccnz .LBB0_2072
	s_bitcmp1_b32 s18, 0
	s_cselect_b32 s16, 0x5800, 0
	s_and_saveexec_b64 s[14:15], s[4:5]
	s_cbranch_execz .LBB0_2071
	v_lshl_add_u32 v2, v249, 1, s16
	s_waitcnt vmcnt(3)
	ds_write_b128 v2, v[128:131]
.LBB0_2071:
	s_or_b64 exec, exec, s[14:15]
	v_lshl_add_u32 v2, v164, 1, s16
	s_waitcnt vmcnt(2)
	ds_write_b128 v2, v[132:135] offset:13312
